# delta scan: decay gate a precomputed for all 2064 tokens into an LDS table in the item preheader, sigmoid gate computed at the start of the chunk preprocess; per-chunk gate tail removed
# baseline (speedup 1.0000x reference)
;   __device__ __forceinline__ float* O() const { return (float*)(GAS float*)out; }
;   __device__ __forceinline__ unsigned char* W() const { return (unsigned char*)(GAS unsigned char*)ws; }
; __device__ __forceinline__ float bflo(unsigned u) { return __uint_as_float(u << 16); }
; __device__ __forceinline__ float sigmoidf_(float x) { return __builtin_amdgcn_rcpf(1.0f + __expf(-x)); }
; __device__ __forceinline__ float softplusf_(float x) { return fmaxf(x, 0.f) + __logf(1.0f + __expf(-fabsf(x))); }
; template <int MIX>
; __device__ __forceinline__ void scan_part(const Params& p, const int layer, const int smp, const int b0, const int bstep, const int bend, const int h, const int part, char* lds, const int tid) {
;     ...
;   for (int b = b0; b < bend; b += bstep) {
;   const int row0 = smp ? MP + b * 4 : b * TPR;
;   const bf16_t* Pb = (const bf16_t*)(p.W() + OFF_P) + (size_t)row0 * DINP;
;   bf16_t* Ob = (bf16_t*)p.O() + (size_t)row0 * 1024 + MIX * 256 + h * 64 + part * CW;
;   float* PS = (float*)((unsigned char*)p.O() + DOUT_PS) + (size_t)row0 * 128 + (MIX * 4 + h) * 8 + part * 2;
;   uint4 R0 = make_uint4(0, 0, 0, 0), R1 = R0, R4 = R0, R5 = R0; uint2 R2 = make_uint2(0, 0); unsigned ex0 = 0, ex1 = 0;
;   load_chunk_fn<MIX, VN>(p.W(), Pb, tt, T, h, vcol, sub, posb, R0, R1, R2, R4, R5, ex0, ex1);
;     ...
;           const float be = sigmoidf_(bflo(ex0)), al = bflo(ex1);
;           const float a = __expf(-Aexp * softplusf_(al + dtb));
.LBB0_420:
	s_or_b64 exec, exec, s[38:39]
	v_readlane_b32 s48, v254, 17
	v_readlane_b32 s49, v254, 18
	s_lshl_b32 s26, s46, 3
	s_lshl_b64 s[42:43], s[48:49], 11
	s_add_u32 s29, s72, s42
	s_addc_u32 s44, s73, s43
	s_lshl_b64 s[42:43], s[34:35], 1
	s_add_u32 s29, s29, s42
	s_addc_u32 s43, s44, s43
	s_lshl_b32 s42, s25, 1
	s_add_u32 s42, s29, s42
	v_ashrrev_i32_e32 v0, 4, v130
	v_lshrrev_b32_e32 v1, 4, v130
	s_mov_b32 s27, s49
	v_lshlrev_b32_e32 v137, 2, v79
	v_lshlrev_b32_e32 v2, 2, v77
	s_addc_u32 s43, s43, 0
	s_lshl_b64 s[44:45], s[48:49], 9
	v_readlane_b32 s48, v253, 33
	v_bfi_b32 v134, -4, v0, v1
	v_sub_u32_e32 v140, v137, v2
	v_readlane_b32 s49, v253, 34
	s_add_u32 s29, s48, s44
	s_waitcnt vmcnt(17)
	v_mul_f32_e32 v2, 0x3fb8aa3b, v76
	v_lshlrev_b32_e32 v0, 2, v0
	v_bfe_u32 v80, v130, 4, 2
	v_and_b32_e32 v135, 15, v130
	s_addc_u32 s44, s49, s45
	s_lshl_b64 s[26:27], s[26:27], 2
	v_exp_f32_e32 v146, v2
	v_lshlrev_b32_e32 v2, 1, v79
	v_and_b32_e32 v0, -16, v0
	s_movk_i32 s23, 0x120
	s_add_u32 s26, s29, s26
	v_lshl_add_u64 v[100:101], s[42:43], 0, v[2:3]
	v_lshl_add_u32 v2, v135, 6, v0
	v_lshlrev_b32_e32 v76, 2, v80
	v_mul_lo_u32 v138, v131, s23
	s_addc_u32 s27, s44, s27
	s_lshl_b32 s29, s24, 3
	v_or_b32_e32 v2, v2, v76
	v_lshl_add_u32 v139, v78, 1, v138
	v_mul_i32_i24_e32 v1, -12, v77
	v_mad_u32_u24 v78, v77, 12, v140
	v_lshl_or_b32 v141, v131, 10, v137
	v_mul_u32_u24_e32 v81, 24, v77
	v_cmp_eq_u32_e64 s[38:39], 0, v77
	v_lshlrev_b32_e32 v145, 4, v135
	v_lshlrev_b32_e32 v77, 6, v131
	s_add_u32 s48, s26, s29
	v_add_u32_e32 v147, 0x7c80, v2
	v_or_b32_e32 v0, v0, v76
	v_mov_b32_e32 v2, v3
	v_lshlrev_b32_e32 v136, 2, v134
	s_mov_b32 s23, 0
	v_lshlrev_b32_e32 v142, 4, v131
	v_cmp_gt_i32_e64 s[40:41], 54, v130
	v_lshlrev_b32_e32 v143, 4, v130
	v_lshlrev_b32_e32 v144, 2, v135
	s_addc_u32 s49, s27, 0
	v_add_u32_e32 v148, 0x700, v0
	v_or_b32_e32 v149, 0x400, v145
	v_add_u32_e32 v150, v139, v1
	v_add_u32_e32 v151, v78, v138
	v_add_u32_e32 v152, v141, v81
	v_add_u32_e32 v153, v137, v77
	v_mov_b64_e32 v[104:105], v[2:3]
	v_mov_b64_e32 v[102:103], v[2:3]
	s_mov_b32 s50, 0xbfb8aa3b
	s_mov_b32 s51, 0x3f317217
	s_mov_b32 s52, 0x7f800000
	s_lshl_b32 s70, s46, 1
	s_mov_b32 s71, 0
	s_movk_i32 s53, 0x810
	s_mov_b64 s[42:43], exec
	v_add_u32_e32 v194, 0x0, v130
	v_cmp_gt_i32_e64 s[76:77], s53, v194
	s_and_b64 exec, s[42:43], s[76:77]
	v_mov_b64_e32 v[192:193], s[2:3]
	v_mad_i64_i32 v[192:193], s[26:27], v194, s68, v[192:193]
	v_lshl_add_u64 v[192:193], v[192:193], 0, s[70:71]
	global_load_ushort v183, v[192:193], off offset:1544
	v_add_u32_e32 v195, 0x100, v130
	v_cmp_gt_i32_e64 s[76:77], s53, v195
	s_and_b64 exec, s[42:43], s[76:77]
	v_mov_b64_e32 v[192:193], s[2:3]
	v_mad_i64_i32 v[192:193], s[26:27], v195, s68, v[192:193]
	v_lshl_add_u64 v[192:193], v[192:193], 0, s[70:71]
	global_load_ushort v184, v[192:193], off offset:1544
	v_add_u32_e32 v196, 0x200, v130
	v_cmp_gt_i32_e64 s[76:77], s53, v196
	s_and_b64 exec, s[42:43], s[76:77]
	v_mov_b64_e32 v[192:193], s[2:3]
	v_mad_i64_i32 v[192:193], s[26:27], v196, s68, v[192:193]
	v_lshl_add_u64 v[192:193], v[192:193], 0, s[70:71]
	global_load_ushort v185, v[192:193], off offset:1544
	v_add_u32_e32 v197, 0x300, v130
	v_cmp_gt_i32_e64 s[76:77], s53, v197
	s_and_b64 exec, s[42:43], s[76:77]
	v_mov_b64_e32 v[192:193], s[2:3]
	v_mad_i64_i32 v[192:193], s[26:27], v197, s68, v[192:193]
	v_lshl_add_u64 v[192:193], v[192:193], 0, s[70:71]
	global_load_ushort v186, v[192:193], off offset:1544
	v_add_u32_e32 v198, 0x400, v130
	v_cmp_gt_i32_e64 s[76:77], s53, v198
	s_and_b64 exec, s[42:43], s[76:77]
	v_mov_b64_e32 v[192:193], s[2:3]
	v_mad_i64_i32 v[192:193], s[26:27], v198, s68, v[192:193]
	v_lshl_add_u64 v[192:193], v[192:193], 0, s[70:71]
	global_load_ushort v187, v[192:193], off offset:1544
	v_add_u32_e32 v199, 0x500, v130
	v_cmp_gt_i32_e64 s[76:77], s53, v199
	s_and_b64 exec, s[42:43], s[76:77]
	v_mov_b64_e32 v[192:193], s[2:3]
	v_mad_i64_i32 v[192:193], s[26:27], v199, s68, v[192:193]
	v_lshl_add_u64 v[192:193], v[192:193], 0, s[70:71]
	global_load_ushort v188, v[192:193], off offset:1544
	v_add_u32_e32 v200, 0x600, v130
	v_cmp_gt_i32_e64 s[76:77], s53, v200
	s_and_b64 exec, s[42:43], s[76:77]
	v_mov_b64_e32 v[192:193], s[2:3]
	v_mad_i64_i32 v[192:193], s[26:27], v200, s68, v[192:193]
	v_lshl_add_u64 v[192:193], v[192:193], 0, s[70:71]
	global_load_ushort v189, v[192:193], off offset:1544
	v_add_u32_e32 v201, 0x700, v130
	v_cmp_gt_i32_e64 s[76:77], s53, v201
	s_and_b64 exec, s[42:43], s[76:77]
	v_mov_b64_e32 v[192:193], s[2:3]
	v_mad_i64_i32 v[192:193], s[26:27], v201, s68, v[192:193]
	v_lshl_add_u64 v[192:193], v[192:193], 0, s[70:71]
	global_load_ushort v190, v[192:193], off offset:1544
	v_add_u32_e32 v202, 0x800, v130
	v_cmp_gt_i32_e64 s[76:77], s53, v202
	s_and_b64 exec, s[42:43], s[76:77]
	v_mov_b64_e32 v[192:193], s[2:3]
	v_mad_i64_i32 v[192:193], s[26:27], v202, s68, v[192:193]
	v_lshl_add_u64 v[192:193], v[192:193], 0, s[70:71]
	global_load_ushort v191, v[192:193], off offset:1544
	s_mov_b64 exec, s[42:43]
	s_waitcnt vmcnt(0)
; __device__ __forceinline__ float bflo(unsigned u) { return __uint_as_float(u << 16); }
; __device__ __forceinline__ float sigmoidf_(float x) { return __builtin_amdgcn_rcpf(1.0f + __expf(-x)); }
; __device__ __forceinline__ float softplusf_(float x) { return fmaxf(x, 0.f) + __logf(1.0f + __expf(-fabsf(x))); }
; template <int MIX>
; __device__ __forceinline__ void scan_part(const Params& p, const int layer, const int smp, const int b0, const int bstep, const int bend, const int h, const int part, char* lds, const int tid) {
;     ...
;           const float be = sigmoidf_(bflo(ex0)), al = bflo(ex1);
;           const float a = __expf(-Aexp * softplusf_(al + dtb));
	v_lshlrev_b32_e32 v203, 16, v183
	v_lshlrev_b32_e32 v206, 16, v184
	v_lshlrev_b32_e32 v235, 16, v185
	v_add_f32_e32 v203, v132, v203
	v_add_f32_e32 v206, v132, v206
	v_add_f32_e32 v235, v132, v235
	v_max_f32_e32 v204, 0, v203
	v_max_f32_e32 v233, 0, v206
	v_max_f32_e32 v236, 0, v235
	v_mul_f32_e64 v203, |v203|, s50
	v_mul_f32_e64 v206, |v206|, s50
	v_mul_f32_e64 v235, |v235|, s50
	v_exp_f32_e32 v203, v203
	v_exp_f32_e32 v206, v206
	v_exp_f32_e32 v235, v235
	v_add_f32_e32 v203, 1.0, v203
	v_add_f32_e32 v206, 1.0, v206
	v_add_f32_e32 v235, 1.0, v235
	v_cmp_gt_f32_e64 s[54:55], s92, v203
	v_cmp_gt_f32_e64 s[56:57], s92, v206
	v_cmp_gt_f32_e64 s[60:61], s92, v235
	s_nop 1
	s_nop 1
	s_nop 1
	v_cndmask_b32_e64 v205, 0, 32, s[54:55]
	v_cndmask_b32_e64 v234, 0, 32, s[56:57]
	v_cndmask_b32_e64 v237, 0, 32, s[60:61]
	v_ldexp_f32 v203, v203, v205
	v_ldexp_f32 v206, v206, v234
	v_ldexp_f32 v235, v235, v237
	v_log_f32_e32 v203, v203
	v_log_f32_e32 v206, v206
	v_log_f32_e32 v235, v235
	v_mul_f32_e32 v205, 0x3f317217, v203
	v_mul_f32_e32 v234, 0x3f317217, v206
	v_mul_f32_e32 v237, 0x3f317217, v235
	v_fma_f32 v205, v203, s51, -v205
	v_fma_f32 v234, v206, s51, -v234
	v_fma_f32 v237, v235, s51, -v237
	v_fmac_f32_e32 v205, 0x3377d1cf, v203
	v_fmac_f32_e32 v234, 0x3377d1cf, v206
	v_fmac_f32_e32 v237, 0x3377d1cf, v235
	v_fmac_f32_e32 v205, 0x3f317217, v203
	v_fmac_f32_e32 v234, 0x3f317217, v206
	v_fmac_f32_e32 v237, 0x3f317217, v235
	v_cmp_lt_f32_e64 s[62:63], |v203|, s52
	v_cmp_lt_f32_e64 s[80:81], |v206|, s52
	v_cmp_lt_f32_e64 s[82:83], |v235|, s52
	s_nop 1
	s_nop 1
	s_nop 1
	v_cndmask_b32_e64 v203, v203, v205, s[62:63]
	v_cndmask_b32_e64 v206, v206, v234, s[80:81]
	v_cndmask_b32_e64 v235, v235, v237, s[82:83]
	v_cndmask_b32_e64 v205, 0, v163, s[54:55]
	v_cndmask_b32_e64 v234, 0, v163, s[56:57]
	v_cndmask_b32_e64 v237, 0, v163, s[60:61]
	v_sub_f32_e32 v203, v203, v205
	v_sub_f32_e32 v206, v206, v234
	v_sub_f32_e32 v235, v235, v237
	v_add_f32_e32 v203, v204, v203
	v_add_f32_e32 v206, v233, v206
	v_add_f32_e32 v235, v236, v235
	v_mul_f32_e32 v203, v203, v146
	v_mul_f32_e32 v206, v206, v146
	v_mul_f32_e32 v235, v235, v146
	v_mul_f32_e32 v203, 0xbfb8aa3b, v203
	v_mul_f32_e32 v206, 0xbfb8aa3b, v206
	v_mul_f32_e32 v235, 0xbfb8aa3b, v235
	v_exp_f32_e32 v212, v203
	v_exp_f32_e32 v214, v206
	v_exp_f32_e32 v216, v235
	v_lshlrev_b32_e32 v203, 16, v186
	v_lshlrev_b32_e32 v206, 16, v187
	v_lshlrev_b32_e32 v235, 16, v188
	v_add_f32_e32 v203, v132, v203
	v_add_f32_e32 v206, v132, v206
	v_add_f32_e32 v235, v132, v235
	v_max_f32_e32 v204, 0, v203
	v_max_f32_e32 v233, 0, v206
	v_max_f32_e32 v236, 0, v235
	v_mul_f32_e64 v203, |v203|, s50
	v_mul_f32_e64 v206, |v206|, s50
	v_mul_f32_e64 v235, |v235|, s50
	v_exp_f32_e32 v203, v203
	v_exp_f32_e32 v206, v206
	v_exp_f32_e32 v235, v235
	v_add_f32_e32 v203, 1.0, v203
	v_add_f32_e32 v206, 1.0, v206
	v_add_f32_e32 v235, 1.0, v235
	v_cmp_gt_f32_e64 s[54:55], s92, v203
	v_cmp_gt_f32_e64 s[56:57], s92, v206
	v_cmp_gt_f32_e64 s[60:61], s92, v235
	s_nop 1
	s_nop 1
	s_nop 1
	v_cndmask_b32_e64 v205, 0, 32, s[54:55]
	v_cndmask_b32_e64 v234, 0, 32, s[56:57]
	v_cndmask_b32_e64 v237, 0, 32, s[60:61]
	v_ldexp_f32 v203, v203, v205
	v_ldexp_f32 v206, v206, v234
	v_ldexp_f32 v235, v235, v237
	v_log_f32_e32 v203, v203
	v_log_f32_e32 v206, v206
	v_log_f32_e32 v235, v235
	v_mul_f32_e32 v205, 0x3f317217, v203
	v_mul_f32_e32 v234, 0x3f317217, v206
	v_mul_f32_e32 v237, 0x3f317217, v235
	v_fma_f32 v205, v203, s51, -v205
	v_fma_f32 v234, v206, s51, -v234
	v_fma_f32 v237, v235, s51, -v237
	v_fmac_f32_e32 v205, 0x3377d1cf, v203
	v_fmac_f32_e32 v234, 0x3377d1cf, v206
	v_fmac_f32_e32 v237, 0x3377d1cf, v235
	v_fmac_f32_e32 v205, 0x3f317217, v203
	v_fmac_f32_e32 v234, 0x3f317217, v206
	v_fmac_f32_e32 v237, 0x3f317217, v235
	v_cmp_lt_f32_e64 s[62:63], |v203|, s52
	v_cmp_lt_f32_e64 s[80:81], |v206|, s52
	v_cmp_lt_f32_e64 s[82:83], |v235|, s52
	s_nop 1
	s_nop 1
	s_nop 1
	v_cndmask_b32_e64 v203, v203, v205, s[62:63]
	v_cndmask_b32_e64 v206, v206, v234, s[80:81]
	v_cndmask_b32_e64 v235, v235, v237, s[82:83]
	v_cndmask_b32_e64 v205, 0, v163, s[54:55]
	v_cndmask_b32_e64 v234, 0, v163, s[56:57]
	v_cndmask_b32_e64 v237, 0, v163, s[60:61]
; __device__ __forceinline__ float bflo(unsigned u) { return __uint_as_float(u << 16); }
; __device__ __forceinline__ float sigmoidf_(float x) { return __builtin_amdgcn_rcpf(1.0f + __expf(-x)); }
; __device__ __forceinline__ float softplusf_(float x) { return fmaxf(x, 0.f) + __logf(1.0f + __expf(-fabsf(x))); }
; template <int MIX>
; __device__ __forceinline__ void scan_part(const Params& p, const int layer, const int smp, const int b0, const int bstep, const int bend, const int h, const int part, char* lds, const int tid) {
;     ...
;   __syncthreads();
;     ...
;           const float be = sigmoidf_(bflo(ex0)), al = bflo(ex1);
;           const float a = __expf(-Aexp * softplusf_(al + dtb));
;           *(f32x4*)(scal + tt * 4) = (f32x4){a, be, qk, 0.f};
	v_sub_f32_e32 v203, v203, v205
	v_sub_f32_e32 v206, v206, v234
	v_sub_f32_e32 v235, v235, v237
	v_add_f32_e32 v203, v204, v203
	v_add_f32_e32 v206, v233, v206
	v_add_f32_e32 v235, v236, v235
	v_mul_f32_e32 v203, v203, v146
	v_mul_f32_e32 v206, v206, v146
	v_mul_f32_e32 v235, v235, v146
	v_mul_f32_e32 v203, 0xbfb8aa3b, v203
	v_mul_f32_e32 v206, 0xbfb8aa3b, v206
	v_mul_f32_e32 v235, 0xbfb8aa3b, v235
	v_exp_f32_e32 v218, v203
	v_exp_f32_e32 v220, v206
	v_exp_f32_e32 v222, v235
	v_lshlrev_b32_e32 v203, 16, v189
	v_lshlrev_b32_e32 v206, 16, v190
	v_lshlrev_b32_e32 v235, 16, v191
	v_add_f32_e32 v203, v132, v203
	v_add_f32_e32 v206, v132, v206
	v_add_f32_e32 v235, v132, v235
	v_max_f32_e32 v204, 0, v203
	v_max_f32_e32 v233, 0, v206
	v_max_f32_e32 v236, 0, v235
	v_mul_f32_e64 v203, |v203|, s50
	v_mul_f32_e64 v206, |v206|, s50
	v_mul_f32_e64 v235, |v235|, s50
	v_exp_f32_e32 v203, v203
	v_exp_f32_e32 v206, v206
	v_exp_f32_e32 v235, v235
	v_add_f32_e32 v203, 1.0, v203
	v_add_f32_e32 v206, 1.0, v206
	v_add_f32_e32 v235, 1.0, v235
	v_cmp_gt_f32_e64 s[54:55], s92, v203
	v_cmp_gt_f32_e64 s[56:57], s92, v206
	v_cmp_gt_f32_e64 s[60:61], s92, v235
	s_nop 1
	s_nop 1
	s_nop 1
	v_cndmask_b32_e64 v205, 0, 32, s[54:55]
	v_cndmask_b32_e64 v234, 0, 32, s[56:57]
	v_cndmask_b32_e64 v237, 0, 32, s[60:61]
	v_ldexp_f32 v203, v203, v205
	v_ldexp_f32 v206, v206, v234
	v_ldexp_f32 v235, v235, v237
	v_log_f32_e32 v203, v203
	v_log_f32_e32 v206, v206
	v_log_f32_e32 v235, v235
	v_mul_f32_e32 v205, 0x3f317217, v203
	v_mul_f32_e32 v234, 0x3f317217, v206
	v_mul_f32_e32 v237, 0x3f317217, v235
	v_fma_f32 v205, v203, s51, -v205
	v_fma_f32 v234, v206, s51, -v234
	v_fma_f32 v237, v235, s51, -v237
	v_fmac_f32_e32 v205, 0x3377d1cf, v203
	v_fmac_f32_e32 v234, 0x3377d1cf, v206
	v_fmac_f32_e32 v237, 0x3377d1cf, v235
	v_fmac_f32_e32 v205, 0x3f317217, v203
	v_fmac_f32_e32 v234, 0x3f317217, v206
	v_fmac_f32_e32 v237, 0x3f317217, v235
	v_cmp_lt_f32_e64 s[62:63], |v203|, s52
	v_cmp_lt_f32_e64 s[80:81], |v206|, s52
	v_cmp_lt_f32_e64 s[82:83], |v235|, s52
	s_nop 1
	s_nop 1
	s_nop 1
	v_cndmask_b32_e64 v203, v203, v205, s[62:63]
	v_cndmask_b32_e64 v206, v206, v234, s[80:81]
	v_cndmask_b32_e64 v235, v235, v237, s[82:83]
	v_cndmask_b32_e64 v205, 0, v163, s[54:55]
	v_cndmask_b32_e64 v234, 0, v163, s[56:57]
	v_cndmask_b32_e64 v237, 0, v163, s[60:61]
	v_sub_f32_e32 v203, v203, v205
	v_sub_f32_e32 v206, v206, v234
	v_sub_f32_e32 v235, v235, v237
	v_add_f32_e32 v203, v204, v203
	v_add_f32_e32 v206, v233, v206
	v_add_f32_e32 v235, v236, v235
	v_mul_f32_e32 v203, v203, v146
	v_mul_f32_e32 v206, v206, v146
	v_mul_f32_e32 v235, v235, v146
	v_mul_f32_e32 v203, 0xbfb8aa3b, v203
	v_mul_f32_e32 v206, 0xbfb8aa3b, v206
	v_mul_f32_e32 v235, 0xbfb8aa3b, v235
	v_exp_f32_e32 v224, v203
	v_exp_f32_e32 v226, v206
	v_exp_f32_e32 v228, v235
	s_nop 1
	v_cmp_gt_i32_e64 s[76:77], s53, v194
	s_and_b64 exec, s[42:43], s[76:77]
	v_lshlrev_b32_e32 v194, 2, v194
	ds_write_b32 v194, v212 offset:50880
	v_cmp_gt_i32_e64 s[76:77], s53, v195
	s_and_b64 exec, s[42:43], s[76:77]
	v_lshlrev_b32_e32 v195, 2, v195
	ds_write_b32 v195, v214 offset:50880
	v_cmp_gt_i32_e64 s[76:77], s53, v196
	s_and_b64 exec, s[42:43], s[76:77]
	v_lshlrev_b32_e32 v196, 2, v196
	ds_write_b32 v196, v216 offset:50880
	v_cmp_gt_i32_e64 s[76:77], s53, v197
	s_and_b64 exec, s[42:43], s[76:77]
	v_lshlrev_b32_e32 v197, 2, v197
	ds_write_b32 v197, v218 offset:50880
	v_cmp_gt_i32_e64 s[76:77], s53, v198
	s_and_b64 exec, s[42:43], s[76:77]
	v_lshlrev_b32_e32 v198, 2, v198
	ds_write_b32 v198, v220 offset:50880
	v_cmp_gt_i32_e64 s[76:77], s53, v199
	s_and_b64 exec, s[42:43], s[76:77]
	v_lshlrev_b32_e32 v199, 2, v199
	ds_write_b32 v199, v222 offset:50880
	v_cmp_gt_i32_e64 s[76:77], s53, v200
	s_and_b64 exec, s[42:43], s[76:77]
	v_lshlrev_b32_e32 v200, 2, v200
	ds_write_b32 v200, v224 offset:50880
	v_cmp_gt_i32_e64 s[76:77], s53, v201
	s_and_b64 exec, s[42:43], s[76:77]
	v_lshlrev_b32_e32 v201, 2, v201
	ds_write_b32 v201, v226 offset:50880
	v_cmp_gt_i32_e64 s[76:77], s53, v202
	s_and_b64 exec, s[42:43], s[76:77]
	v_lshlrev_b32_e32 v202, 2, v202
	ds_write_b32 v202, v228 offset:50880
	s_mov_b64 exec, s[42:43]
	s_waitcnt vmcnt(0) lgkmcnt(0)
	s_barrier

; __device__ __forceinline__ float bflo(unsigned u) { return __uint_as_float(u << 16); }
; __device__ __forceinline__ float bfhi(unsigned u) { return __uint_as_float(u & 0xffff0000u); }
; __device__ __forceinline__ float siluf_(float x) { return x * __builtin_amdgcn_rcpf(1.0f + __expf(-x)); }
; template <int N, int RS>
; __device__ __forceinline__ void convN(const bf16_t* rawb, const float (&w)[4][N], int tt, int off, float (&x)[N]) {
; #pragma unroll
;   for (int i = 0; i < N; ++i) x[i] = 0.f;
; #pragma unroll
;   for (int j = 0; j < 4; ++j) {
;     float xv[N];
;     if (N == 8) { const uint4 rv = *(const uint4*)(rawb + (tt + j) * RS + off); unpack8(rv, xv); }
;     else if (N == 4) { const uint2 rv = *(const uint2*)(rawb + (tt + j) * RS + off); xv[0] = bflo(rv.x); xv[1] = bfhi(rv.x); xv[2 % N] = bflo(rv.y); xv[3 % N] = bfhi(rv.y); }
;     else { const unsigned rv = *(const unsigned*)(rawb + (tt + j) * RS + off); xv[0] = bflo(rv); xv[1] = bfhi(rv); }
; #pragma unroll
;     for (int i = 0; i < N; ++i) x[i] += w[j][i] * xv[i];
;   }
;   if (N == 2) {
; #pragma unroll
;     for (int i = 0; i < N; ++i) asm volatile("" : "+v"(x[i]));
;   }
; #pragma unroll
;   for (int i = 0; i < N; ++i) x[i] = siluf_(x[i]);
; template <int MIX>
; __device__ __forceinline__ void scan_part(const Params& p, const int layer, const int smp, const int b0, const int bstep, const int bend, const int h, const int part, char* lds, const int tid) {
;     ...
;       if (valid) {
;         float xq[8], xk[8], xv[VN];
;         { float cwv[4][VN];
; #pragma unroll
;           for (int j = 0; j < 4; ++j)
; #pragma unroll
;             for (int i = 0; i < VN; ++i) cwv[j][i] = cwl[j * RS + 128 + sub * VN + i];
;           convN<VN, RS>(rawb, cwv, tt, 128 + sub * VN, xv); }
;         convN<8, RS>(rawb, cwq, tt, sub * 8, xq);
;         convN<8, RS>(rawb, cwk, tt, 64 + sub * 8, xk);
.Ld_top_done:
	s_and_saveexec_b64 s[50:51], s[42:43]
	s_cbranch_execz .LBB0_426
	v_add_u32_e32 v232, s23, v131
	v_lshlrev_b32_e32 v232, 2, v232
	ds_read_b32 v230, v232 offset:50880
	v_lshlrev_b32_e32 v231, 16, v133
	v_mul_f32_e32 v231, 0xbfb8aa3b, v231
	v_add_u32_e32 v2, v140, v138
	v_add_u32_e32 v0, 0x9200, v2
	v_add_u32_e32 v76, 0xbc00, v137
	v_exp_f32_e32 v231, v231
	ds_read2_b32 v[0:1], v0 offset0:64 offset1:136
	ds_read2_b64 v[76:79], v76 offset0:120 offset1:192
	v_add_u32_e32 v80, 0xc000, v137
	v_add_u32_e32 v2, 0x9400, v2
	v_add_f32_e32 v231, 1.0, v231
	ds_read2_b64 v[80:83], v80 offset0:136 offset1:208
	s_waitcnt lgkmcnt(2)
	v_lshlrev_b32_e32 v85, 16, v1
	v_lshlrev_b32_e32 v84, 16, v0
	v_rcp_f32_e32 v231, v231
	s_waitcnt lgkmcnt(1)
	v_mov_b32_e32 v86, v76
	v_mov_b32_e32 v87, v78
	v_pk_mul_f32 v[84:85], v[86:87], v[84:85]
	v_and_b32_e32 v1, 0xffff0000, v1
	v_add_f32_e32 v76, 0, v84
	v_add_f32_e32 v86, v76, v85
	ds_read2_b32 v[84:85], v2 offset0:80 offset1:152
	v_and_b32_e32 v0, 0xffff0000, v0
	v_mov_b32_e32 v78, v77
	v_pk_mul_f32 v[0:1], v[78:79], v[0:1]
	s_waitcnt lgkmcnt(1)
	v_mov_b32_e32 v76, v80
	v_add_f32_e32 v0, 0, v0
	v_add_f32_e32 v2, v0, v1
	s_waitcnt lgkmcnt(0)
	v_lshlrev_b32_e32 v1, 16, v85
	v_lshlrev_b32_e32 v0, 16, v84
	v_mov_b32_e32 v77, v82
	v_pk_mul_f32 v[0:1], v[76:77], v[0:1]
	v_and_b32_e32 v77, 0xffff0000, v85
	v_and_b32_e32 v76, 0xffff0000, v84
	v_mov_b32_e32 v82, v81
	v_add_f32_e32 v0, v86, v0
	v_pk_mul_f32 v[76:77], v[82:83], v[76:77]
	v_add_f32_e32 v0, v0, v1
	v_add_f32_e32 v1, v2, v76
	v_add_f32_e32 v1, v1, v77
	ds_read_b128 v[78:81], v151 offset:37376
	ds_read_b128 v[82:85], v151 offset:37504
	ds_read_b128 v[86:89], v151 offset:37664
	ds_read_b128 v[90:93], v151 offset:37952
	v_mul_f32_e32 v2, 0xbfb8aa3b, v0
	ds_read_b128 v[174:177], v151 offset:38240
	v_exp_f32_e32 v2, v2
	v_mul_f32_e32 v76, 0xbfb8aa3b, v1
	v_exp_f32_e32 v77, v76
	s_waitcnt lgkmcnt(4)
	v_lshlrev_b32_e32 v154, 16, v80
	v_and_b32_e32 v155, 0xffff0000, v80
	v_lshlrev_b32_e32 v94, 16, v78
	v_and_b32_e32 v95, 0xffff0000, v78
	v_lshlrev_b32_e32 v106, 16, v79
	v_and_b32_e32 v107, 0xffff0000, v79
	v_lshlrev_b32_e32 v178, 16, v81
	v_and_b32_e32 v179, 0xffff0000, v81
	ds_read_b128 v[78:81], v151 offset:37792
	s_waitcnt lgkmcnt(3)
	v_lshlrev_b32_e32 v180, 16, v86
	v_and_b32_e32 v181, 0xffff0000, v86
	v_lshlrev_b32_e32 v182, 16, v87
	v_and_b32_e32 v183, 0xffff0000, v87
	v_lshlrev_b32_e32 v184, 16, v88
	v_and_b32_e32 v185, 0xffff0000, v88
	v_lshlrev_b32_e32 v186, 16, v89
	v_and_b32_e32 v187, 0xffff0000, v89
	ds_read_b128 v[86:89], v151 offset:38080
	s_waitcnt lgkmcnt(3)
	v_lshlrev_b32_e32 v188, 16, v90
	v_and_b32_e32 v189, 0xffff0000, v90
	v_lshlrev_b32_e32 v190, 16, v91
	v_and_b32_e32 v191, 0xffff0000, v91
	v_lshlrev_b32_e32 v192, 16, v92
	v_and_b32_e32 v193, 0xffff0000, v92
	v_lshlrev_b32_e32 v194, 16, v93
	v_and_b32_e32 v195, 0xffff0000, v93
	ds_read_b128 v[90:93], v151 offset:38368
	s_waitcnt vmcnt(2)
	v_pk_fma_f32 v[154:155], v[4:5], v[154:155], 0 op_sel_hi:[1,1,0]
	v_add_f32_e32 v2, 1.0, v2
	s_waitcnt vmcnt(2)
	v_pk_fma_f32 v[154:155], v[12:13], v[184:185], v[154:155]
	s_waitcnt lgkmcnt(3)
	v_lshlrev_b32_e32 v198, 16, v176
	v_and_b32_e32 v199, 0xffff0000, v176
	s_waitcnt vmcnt(2)
	v_pk_fma_f32 v[154:155], v[20:21], v[192:193], v[154:155]
	v_rcp_f32_e32 v76, v2
	v_add_f32_e32 v2, 1.0, v77
	s_waitcnt vmcnt(2)
	v_pk_fma_f32 v[154:155], v[28:29], v[198:199], v[154:155]
	v_rcp_f32_e32 v77, v2
	v_mul_f32_e32 v2, 0xbfb8aa3b, v154
	v_lshlrev_b32_e32 v202, 16, v84
	v_and_b32_e32 v203, 0xffff0000, v84
	s_waitcnt lgkmcnt(0)
	v_lshlrev_b32_e32 v214, 16, v92
	v_and_b32_e32 v215, 0xffff0000, v92
	v_exp_f32_e32 v2, v2
	v_mul_f32_e32 v92, 0xbfb8aa3b, v155
	v_lshlrev_b32_e32 v206, 16, v80
	v_and_b32_e32 v207, 0xffff0000, v80
	v_exp_f32_e32 v158, v92
	s_waitcnt vmcnt(2)
	v_pk_fma_f32 v[192:193], v[36:37], v[202:203], 0 op_sel_hi:[1,1,0]
	v_lshlrev_b32_e32 v210, 16, v88
	v_and_b32_e32 v211, 0xffff0000, v88
	s_waitcnt vmcnt(2)
	v_pk_fma_f32 v[192:193], v[44:45], v[206:207], v[192:193]
	v_add_f32_e32 v2, 1.0, v2
	s_waitcnt vmcnt(2)
	v_pk_fma_f32 v[192:193], v[52:53], v[210:211], v[192:193]
	v_rcp_f32_e32 v184, v2
	s_waitcnt vmcnt(2)
	v_pk_fma_f32 v[192:193], v[60:61], v[214:215], v[192:193]
	v_add_f32_e32 v2, 1.0, v158
	v_mul_f32_e32 v158, 0xbfb8aa3b, v192
	v_exp_f32_e32 v158, v158
	v_mul_f32_e32 v159, 0xbfb8aa3b, v193
	v_exp_f32_e32 v159, v159
	v_pk_fma_f32 v[178:179], v[6:7], v[178:179], 0 op_sel_hi:[1,1,0]
	v_lshlrev_b32_e32 v176, 16, v177
	v_pk_fma_f32 v[178:179], v[14:15], v[186:187], v[178:179]
	v_and_b32_e32 v177, 0xffff0000, v177
	v_rcp_f32_e32 v185, v2
	v_add_f32_e32 v2, 1.0, v158
	v_pk_fma_f32 v[178:179], v[22:23], v[194:195], v[178:179]
	v_rcp_f32_e32 v198, v2
	v_add_f32_e32 v2, 1.0, v159
	v_pk_fma_f32 v[176:177], v[30:31], v[176:177], v[178:179]
	v_rcp_f32_e32 v199, v2
	v_mul_f32_e32 v2, 0xbfb8aa3b, v176
	v_exp_f32_e32 v2, v2
	v_mul_f32_e32 v158, 0xbfb8aa3b, v177
	v_exp_f32_e32 v158, v158
	v_pk_fma_f32 v[94:95], v[8:9], v[94:95], 0 op_sel_hi:[1,1,0]
	v_lshlrev_b32_e32 v196, 16, v174
	v_pk_fma_f32 v[94:95], v[16:17], v[180:181], v[94:95]
	v_and_b32_e32 v197, 0xffff0000, v174
	v_add_f32_e32 v2, 1.0, v2
	v_pk_fma_f32 v[94:95], v[24:25], v[188:189], v[94:95]
	v_rcp_f32_e32 v186, v2
	v_add_f32_e32 v2, 1.0, v158
	v_pk_fma_f32 v[94:95], v[32:33], v[196:197], v[94:95]
	v_rcp_f32_e32 v187, v2
	v_mul_f32_e32 v2, 0xbfb8aa3b, v94
	v_exp_f32_e32 v2, v2
	v_mul_f32_e32 v158, 0xbfb8aa3b, v95
	v_exp_f32_e32 v158, v158
	v_pk_fma_f32 v[106:107], v[10:11], v[106:107], 0 op_sel_hi:[1,1,0]
	v_lshlrev_b32_e32 v174, 16, v175
	v_pk_fma_f32 v[106:107], v[18:19], v[182:183], v[106:107]
; __device__ __forceinline__ float bflo(unsigned u) { return __uint_as_float(u << 16); }
; __device__ __forceinline__ float sigmoidf_(float x) { return __builtin_amdgcn_rcpf(1.0f + __expf(-x)); }
; __device__ __forceinline__ float softplusf_(float x) { return fmaxf(x, 0.f) + __logf(1.0f + __expf(-fabsf(x))); }
; __device__ __forceinline__ float red8d(float x) { x += dpp_x1(x); x += dpp_x2(x); x += dpp_hm(x); return x; }
; template <int MIX>
; __device__ __forceinline__ void scan_part(const Params& p, const int layer, const int smp, const int b0, const int bstep, const int bend, const int h, const int part, char* lds, const int tid) {
;     ...
; #pragma unroll
;         for (int i = 0; i < VN; ++i) dst[192 + sub * VN + i] = xv[i];
;         float ssq = 0.f, ssk = 0.f;
; #pragma unroll
;         for (int i = 0; i < 8; ++i) { ssq += xq[i] * xq[i]; ssk += xk[i] * xk[i]; }
;         ssq = red8d(ssq); ssk = red8d(ssk);
;         const float rq = rsqrtf(ssq + 1e-6f) * 0.125f, rk = rsqrtf(ssk + 1e-6f);
;         float qk = 0.f;
; #pragma unroll
;         for (int i = 0; i < 8; ++i) { xq[i] *= rq; xk[i] *= rk; qk += xq[i] * xk[i]; }
;         qk = red8d(qk);
;         *(f32x4*)(dst + sub * 8) = (f32x4){xq[0], xq[1], xq[2], xq[3]}; *(f32x4*)(dst + sub * 8 + 4) = (f32x4){xq[4], xq[5], xq[6], xq[7]};
;         *(f32x4*)(dst + 64 + sub * 8) = (f32x4){xk[0], xk[1], xk[2], xk[3]}; *(f32x4*)(dst + 64 + sub * 8 + 4) = (f32x4){xk[4], xk[5], xk[6], xk[7]};
;         if (sub == 0) {
;           const float be = sigmoidf_(bflo(ex0)), al = bflo(ex1);
;           const float a = __expf(-Aexp * softplusf_(al + dtb));
;           *(f32x4*)(scal + tt * 4) = (f32x4){a, be, qk, 0.f};
	v_and_b32_e32 v175, 0xffff0000, v175
	v_pk_fma_f32 v[106:107], v[26:27], v[190:191], v[106:107]
	v_add_f32_e32 v2, 1.0, v2
	v_pk_fma_f32 v[106:107], v[34:35], v[174:175], v[106:107]
	v_rcp_f32_e32 v180, v2
	v_add_f32_e32 v2, 1.0, v158
	v_mul_f32_e32 v158, 0xbfb8aa3b, v106
	v_exp_f32_e32 v158, v158
	v_mul_f32_e32 v159, 0xbfb8aa3b, v107
	v_lshlrev_b32_e32 v84, 16, v85
	v_and_b32_e32 v85, 0xffff0000, v85
	v_exp_f32_e32 v159, v159
	v_lshlrev_b32_e32 v80, 16, v81
	v_and_b32_e32 v81, 0xffff0000, v81
	v_pk_fma_f32 v[84:85], v[38:39], v[84:85], 0 op_sel_hi:[1,1,0]
	v_lshlrev_b32_e32 v88, 16, v89
	v_and_b32_e32 v89, 0xffff0000, v89
	v_pk_fma_f32 v[80:81], v[46:47], v[80:81], v[84:85]
	v_lshlrev_b32_e32 v92, 16, v93
	v_and_b32_e32 v93, 0xffff0000, v93
	v_rcp_f32_e32 v181, v2
	v_add_f32_e32 v2, 1.0, v158
	v_pk_fma_f32 v[80:81], v[54:55], v[88:89], v[80:81]
	v_rcp_f32_e32 v174, v2
	v_add_f32_e32 v2, 1.0, v159
	v_pk_fma_f32 v[80:81], v[62:63], v[92:93], v[80:81]
	v_rcp_f32_e32 v175, v2
	v_mul_f32_e32 v2, 0xbfb8aa3b, v80
	v_exp_f32_e32 v2, v2
	v_mul_f32_e32 v84, 0xbfb8aa3b, v81
	v_exp_f32_e32 v89, v84
	v_lshlrev_b32_e32 v200, 16, v82
	v_and_b32_e32 v201, 0xffff0000, v82
	v_lshlrev_b32_e32 v204, 16, v78
	v_and_b32_e32 v205, 0xffff0000, v78
	v_add_f32_e32 v2, 1.0, v2
	v_pk_fma_f32 v[92:93], v[40:41], v[200:201], 0 op_sel_hi:[1,1,0]
	v_lshlrev_b32_e32 v82, 16, v83
	v_and_b32_e32 v83, 0xffff0000, v83
	v_lshlrev_b32_e32 v208, 16, v86
	v_and_b32_e32 v209, 0xffff0000, v86
	v_rcp_f32_e32 v88, v2
	v_add_f32_e32 v2, 1.0, v89
	v_pk_fma_f32 v[92:93], v[48:49], v[204:205], v[92:93]
	v_lshlrev_b32_e32 v78, 16, v79
	v_and_b32_e32 v79, 0xffff0000, v79
	v_lshlrev_b32_e32 v212, 16, v90
	v_and_b32_e32 v213, 0xffff0000, v90
	v_rcp_f32_e32 v89, v2
	v_pk_fma_f32 v[92:93], v[56:57], v[208:209], v[92:93]
	v_pk_fma_f32 v[82:83], v[42:43], v[82:83], 0 op_sel_hi:[1,1,0]
	v_lshlrev_b32_e32 v86, 16, v87
	v_and_b32_e32 v87, 0xffff0000, v87
	s_waitcnt vmcnt(2)
	v_pk_fma_f32 v[92:93], v[64:65], v[212:213], v[92:93]
	v_pk_fma_f32 v[78:79], v[50:51], v[78:79], v[82:83]
	v_lshlrev_b32_e32 v90, 16, v91
	v_and_b32_e32 v91, 0xffff0000, v91
	v_mul_f32_e32 v2, 0xbfb8aa3b, v92
	v_pk_fma_f32 v[78:79], v[58:59], v[86:87], v[78:79]
	v_exp_f32_e32 v2, v2
	v_mul_f32_e32 v158, 0xbfb8aa3b, v93
	v_pk_fma_f32 v[78:79], v[66:67], v[90:91], v[78:79]
	v_pk_mul_f32 v[106:107], v[106:107], v[174:175]
	v_exp_f32_e32 v158, v158
	v_pk_mul_f32 v[174:175], v[80:81], v[88:89]
	v_mul_f32_e32 v81, 0xbfb8aa3b, v78
	v_exp_f32_e32 v82, v81
	v_mul_f32_e32 v81, 0xbfb8aa3b, v79
	v_exp_f32_e32 v83, v81
	v_add_f32_e32 v2, 1.0, v2
	v_rcp_f32_e32 v80, v2
	v_add_f32_e32 v2, 1.0, v158
	v_rcp_f32_e32 v81, v2
	v_add_f32_e32 v2, 1.0, v82
	v_rcp_f32_e32 v82, v2
	v_add_f32_e32 v2, 1.0, v83
	v_rcp_f32_e32 v83, v2
	v_pk_mul_f32 v[94:95], v[94:95], v[180:181]
	v_pk_mul_f32 v[88:89], v[92:93], v[80:81]
	v_pk_mul_f32 v[180:181], v[94:95], v[94:95]
	v_pk_mul_f32 v[80:81], v[88:89], v[88:89]
	v_pk_mul_f32 v[90:91], v[78:79], v[82:83]
	v_pk_mul_f32 v[84:85], v[106:107], v[106:107]
	v_pk_mul_f32 v[78:79], v[90:91], v[90:91]
	v_mov_b32_e32 v82, v80
	v_mov_b32_e32 v83, v180
	v_mov_b32_e32 v180, v81
	v_pk_mul_f32 v[154:155], v[154:155], v[184:185]
	v_pk_mul_f32 v[192:193], v[192:193], v[198:199]
	v_pk_add_f32 v[80:81], v[82:83], v[180:181]
	v_mov_b32_e32 v82, v78
	v_mov_b32_e32 v83, v84
	v_pk_mul_f32 v[184:185], v[154:155], v[154:155]
	v_pk_mul_f32 v[178:179], v[192:193], v[192:193]
	v_pk_add_f32 v[80:81], v[80:81], v[82:83]
	v_mov_b32_e32 v84, v79
	v_pk_mul_f32 v[176:177], v[176:177], v[186:187]
	v_pk_add_f32 v[78:79], v[84:85], v[80:81]
	v_mov_b32_e32 v80, v178
	v_mov_b32_e32 v81, v184
	v_pk_mul_f32 v[182:183], v[176:177], v[176:177]
	v_pk_mul_f32 v[86:87], v[174:175], v[174:175]
	v_pk_add_f32 v[78:79], v[80:81], v[78:79]
	v_mov_b32_e32 v184, v179
	v_pk_add_f32 v[78:79], v[184:185], v[78:79]
	v_mov_b32_e32 v80, v86
	v_mov_b32_e32 v81, v182
	v_pk_add_f32 v[78:79], v[80:81], v[78:79]
	v_mov_b32_e32 v182, v87
	v_pk_add_f32 v[78:79], v[182:183], v[78:79]
	s_mov_b32 s44, 0x358637bd
	v_pk_mul_f32 v[0:1], v[0:1], v[76:77]
	v_mov_b32_dpp v81, v79 quad_perm:[1,0,3,2] row_mask:0xf bank_mask:0xf bound_ctrl:1
	v_mov_b32_dpp v80, v78 quad_perm:[1,0,3,2] row_mask:0xf bank_mask:0xf bound_ctrl:1
	v_pk_add_f32 v[78:79], v[78:79], v[80:81]
	ds_write_b64 v141, v[0:1] offset:768
	s_nop 0
	v_mov_b32_dpp v81, v79 quad_perm:[2,3,0,1] row_mask:0xf bank_mask:0xf bound_ctrl:1
	v_mov_b32_dpp v80, v78 quad_perm:[2,3,0,1] row_mask:0xf bank_mask:0xf bound_ctrl:1
	v_pk_add_f32 v[78:79], v[78:79], v[80:81]
	s_nop 1
	v_mov_b32_dpp v81, v79 row_half_mirror row_mask:0xf bank_mask:0xf bound_ctrl:1
	v_mov_b32_dpp v80, v78 row_half_mirror row_mask:0xf bank_mask:0xf bound_ctrl:1
	v_pk_add_f32 v[78:79], v[78:79], v[80:81]
	s_nop 0
	v_pk_add_f32 v[78:79], v[78:79], s[44:45] op_sel_hi:[1,0]
	s_nop 0
	v_mul_f32_e32 v2, 0x4b800000, v79
	v_cmp_gt_f32_e32 vcc, s92, v79
	s_nop 1
	v_cndmask_b32_e32 v2, v79, v2, vcc
	v_rsq_f32_e32 v2, v2
	s_nop 0
	v_mul_f32_e32 v0, 0x45800000, v2
	v_cndmask_b32_e32 v0, v2, v0, vcc
	v_mul_f32_e32 v0, 0x3e000000, v0
	v_pk_mul_f32 v[76:77], v[94:95], v[0:1] op_sel_hi:[1,0]
	v_mul_f32_e32 v1, 0x4b800000, v78
	v_cmp_gt_f32_e32 vcc, s92, v78
	s_nop 1
	v_cndmask_b32_e32 v1, v78, v1, vcc
	v_rsq_f32_e32 v1, v1
	s_nop 0
	v_pk_mul_f32 v[78:79], v[106:107], v[0:1] op_sel_hi:[1,0]
	v_pk_mul_f32 v[80:81], v[154:155], v[0:1] op_sel_hi:[1,0]
	v_pk_mul_f32 v[82:83], v[176:177], v[0:1] op_sel_hi:[1,0]
	v_mul_f32_e32 v0, 0x45800000, v1
	v_cndmask_b32_e32 v0, v1, v0, vcc
	v_pk_mul_f32 v[84:85], v[88:89], v[0:1] op_sel_hi:[1,0]
	s_nop 0
	v_pk_mul_f32 v[86:87], v[90:91], v[0:1] op_sel_hi:[1,0]
	s_nop 0
	v_pk_mul_f32 v[88:89], v[192:193], v[0:1] op_sel_hi:[1,0]
	s_nop 0
	v_pk_mul_f32 v[90:91], v[174:175], v[0:1] op_sel_hi:[1,0]
	ds_write_b128 v152, v[76:79]
	ds_write_b128 v152, v[80:83] offset:16
	ds_write_b128 v152, v[84:87] offset:256
	ds_write_b128 v152, v[88:91] offset:272
	s_and_b64 exec, exec, s[38:39]
	s_cbranch_execz .LBB0_426
	v_mov_b32_e32 v2, 0
	s_waitcnt lgkmcnt(0)
	v_mov_b32_e32 v0, v230
	v_mov_b32_e32 v1, v231
	ds_write_b128 v142, v[0:3] offset:36864
